# speedup vs baseline: 1.0040x; 1.0023x over previous
; __device__ __forceinline__ float bf2f(u16 h) { return __uint_as_float(((unsigned)h) << 16); }
; template <int DUMMY>
; __device__ void ssd_item(const Params& p, int item) {
;     ...
;     {
; #pragma unroll
;       for (int i = 0; i < 2; ++i) {
;         int idx = tid + i * NT;
;         *(i32x4*)(Bs + (idx >> 4) * 136 + (idx & 15) * 8) = rBs[i];
;         *(i32x4*)(Cs + (idx >> 4) * 136 + (idx & 15) * 8) = rCs[i];
;         int c8 = idx >> 6, ll = idx & 63;
; #pragma unroll
;         for (int e = 0; e < 4; ++e) {
;           unsigned u = (unsigned)rBT[i][e];
;           BTs[(c8 * 8 + 2 * e) * 72 + ll] = (u16)(u & 0xffffu);
;           BTs[(c8 * 8 + 2 * e + 1) * 72 + ll] = (u16)(u >> 16);
;         }
;       }
;       {
;         float w0 = cwX[0 * 32 + chg], w1 = cwX[1 * 32 + chg], w2 = cwX[2 * 32 + chg], w3 = cwX[3 * 32 + chg], bx = cwX[4 * 32 + chg];
;         float raw[7];
; #pragma unroll
;         for (int i = 0; i < 7; ++i) raw[i] = bf2f(rX[i]);
;         const float cs63 = cs[63];
;         float4 dt4 = *(const float4*)(dv + l0), cs4 = *(const float4*)(cs + l0);
;         float dts[4] = {dt4.x, dt4.y, dt4.z, dt4.w}, css[4] = {cs4.x, cs4.y, cs4.z, cs4.w};
.LBB0_1033:
	s_bfe_i32 s3, s76, 0x10000
	s_and_b32 s3, s3, 0x15800
	s_cmp_lg_u64 s[4:5], 0
	s_cbranch_scc0 .Lssd_noprio
	s_setprio 1
.Lssd_noprio:
	v_lshl_or_b32 v32, v59, 1, s3
	s_lshl_b32 s31, s97, 8
	ds_write_b128 v116, v[20:23] offset:17408
	v_lshl_add_u32 v20, v146, 1, v32
	s_add_i32 s52, s31, 0x1e200
	ds_write_b128 v20, v[16:19]
	ds_write_b16 v52, v12 offset:34816
	ds_write_b16_d16_hi v52, v12 offset:34960
	ds_write_b16 v52, v13 offset:35104
	ds_write_b16_d16_hi v52, v13 offset:35248
	ds_write_b16 v52, v14 offset:35392
	ds_write_b16_d16_hi v52, v14 offset:35536
	ds_write_b16 v52, v15 offset:35680
	ds_write_b16_d16_hi v52, v15 offset:35824
	ds_write_b128 v117, v[24:27] offset:17408
	v_lshl_add_u32 v12, v147, 1, v32
	ds_write_b128 v12, v[28:31]
	ds_write_b16 v54, v8 offset:34816
	ds_write_b16_d16_hi v54, v8 offset:34960
	ds_write_b16 v54, v9 offset:35104
	ds_write_b16_d16_hi v54, v9 offset:35248
	ds_write_b16 v54, v10 offset:35392
	ds_write_b16_d16_hi v54, v10 offset:35536
	ds_write_b16 v54, v11 offset:35680
	ds_write_b16_d16_hi v54, v11 offset:35824
	v_mov_b32_e32 v8, s52
	ds_read2_b32 v[16:17], v115 offset1:32
	ds_read2_b32 v[18:19], v115 offset0:64 offset1:96
	ds_read_b32 v20, v115 offset:512
	ds_read_b32 v21, v8 offset:252
	v_and_b32_e32 v23, 0xffff0000, v173
	v_lshlrev_b32_e32 v22, 16, v173
	v_and_b32_e32 v13, 0xffff0000, v171
	v_lshlrev_b32_e32 v12, 16, v171
	v_add_u32_e32 v31, s31, v114
	v_lshlrev_b32_e32 v24, 16, v101
	s_waitcnt lgkmcnt(0)
	v_pk_fma_f32 v[14:15], v[16:17], v[12:13], v[20:21] op_sel_hi:[0,1,0]
	v_mov_b32_e32 v30, v17
	v_pk_mov_b32 v[12:13], v[12:13], v[22:23] op_sel:[1,0]
	v_lshlrev_b32_e32 v26, 16, v100
	v_pk_fma_f32 v[12:13], v[30:31], v[12:13], v[14:15] op_sel_hi:[0,1,1]
	v_mov_b32_e32 v14, v22
	v_mov_b32_e32 v15, v24
	v_pk_fma_f32 v[12:13], v[18:19], v[14:15], v[12:13] op_sel_hi:[0,1,1]
	v_mov_b32_e32 v32, v19
	v_mov_b32_e32 v14, v24
	v_mov_b32_e32 v15, v26
	v_pk_fma_f32 v[12:13], v[32:33], v[14:15], v[12:13] op_sel_hi:[0,1,1]
	v_and_b32_e32 v25, 0xffff0000, v101
	v_mul_f32_e32 v14, 0xbfb8aa3b, v12
	v_mul_f32_e32 v15, 0xbfb8aa3b, v13
	v_pk_fma_f32 v[16:17], v[16:17], v[22:23], v[20:21] op_sel_hi:[0,1,0]
	v_and_b32_e32 v27, 0xffff0000, v100
	v_exp_f32_e32 v14, v14
	v_exp_f32_e32 v15, v15
	v_pk_fma_f32 v[16:17], v[30:31], v[24:25], v[16:17] op_sel_hi:[0,1,1]
	v_and_b32_e32 v29, 0xffff0000, v42
	v_lshlrev_b32_e32 v28, 16, v42
	v_pk_fma_f32 v[16:17], v[18:19], v[26:27], v[16:17] op_sel_hi:[0,1,1]
	v_pk_fma_f32 v[16:17], v[32:33], v[28:29], v[16:17] op_sel_hi:[0,1,1]
	v_lshl_add_u32 v8, v50, 2, s52
	v_mul_f32_e32 v18, 0xbfb8aa3b, v16
	v_mul_f32_e32 v19, 0xbfb8aa3b, v17
	ds_read_b128 v[8:11], v8
	v_add_f32_e32 v14, 1.0, v14
	v_add_f32_e32 v15, 1.0, v15
	v_exp_f32_e32 v18, v18
	v_exp_f32_e32 v19, v19
	v_rcp_f32_e32 v14, v14
	v_rcp_f32_e32 v15, v15
	v_add_f32_e32 v18, 1.0, v18
	v_add_f32_e32 v19, 1.0, v19
	v_rcp_f32_e32 v18, v18
	v_pk_mul_f32 v[34:35], v[12:13], v[14:15]
	ds_read_b128 v[12:15], v31
	s_waitcnt lgkmcnt(1)
	v_sub_f32_e32 v8, v21, v8
	v_sub_f32_e32 v9, v21, v9
	v_sub_f32_e32 v10, v21, v10
	v_rcp_f32_e32 v19, v19
	v_sub_f32_e32 v11, v21, v11
	v_mul_f32_e32 v8, 0x3fb8aa3b, v8
	v_mul_f32_e32 v9, 0x3fb8aa3b, v9
	v_mul_f32_e32 v10, 0x3fb8aa3b, v10
	v_mul_f32_e32 v11, 0x3fb8aa3b, v11
	v_exp_f32_e32 v8, v8
	v_exp_f32_e32 v9, v9
	v_exp_f32_e32 v10, v10
	v_exp_f32_e32 v11, v11
	s_and_b32 s30, s76, 1
	s_cmp_eq_u32 s30, 0
	s_mov_b32 s30, 0xf400
	v_pk_mul_f32 v[16:17], v[16:17], v[18:19]
	s_cselect_b32 s77, s30, 0x1ae00
	s_waitcnt lgkmcnt(0)
; template <int DUMMY>
; __device__ void ssd_item(const Params& p, int item) {
;     ...
;         *(i32x2*)(xT + chg * 72 + l0) = i32x2{(int)pack2(vx[0], vx[1]), (int)pack2(vx[2], vx[3])};
;         *(i32x2*)(xdT + chg * 72 + l0) = i32x2{(int)pack2(vd[0], vd[1]), (int)pack2(vd[2], vd[3])};
;         *(i32x2*)(xwT + chg * 72 + l0) = i32x2{(int)pack2(vw[0], vw[1]), (int)pack2(vw[2], vw[3])};
;       }
;     }
; #pragma unroll
;     for (int j = 0; j < 2; ++j)
; #pragma unroll
;       for (int r = 0; r < 4; ++r) Sb[(pf * 16 + g4 * 4 + r) * 136 + (nf0 + j) * 16 + fr] = f2bf(accS[j][r]);
; #pragma unroll
;     for (int r = 0; r < 4; ++r) zcur[r] = znext[r];
;     if (c > 1) {
;       const size_t yi = (tb + (c - 2) * 64 + (tid >> 3)) * 4096 + h * 64 + ph * 32 + (tid & 7) * 4;
;       *(i32x2*)(zyo + (yi & omask)) = ypend;
;     }
;     if (c + 1 < 128) {
;       load_raw(c + 1);
;       const size_t zn = zbase + (size_t)64 * 4096;
; #pragma unroll
;       for (int r = 0; r < 4; ++r) znext[r] = zy[zn + (size_t)r * 4096];
;       if (wid == 0) {
;         float dt_use = dt_n;
;         if (c + 2 < 128) dt_n = dtb[(tb + (c + 2) * 64 + lane) * 64 + h];
;         write_cs(dt_use, nxt3);
	v_pk_mul_f32 v[12:13], v[12:13], v[34:35]
	v_pk_mul_f32 v[14:15], v[14:15], v[16:17]
	s_mov_b32 s30, 0xd000
	v_pk_mul_f32 v[8:9], v[8:9], v[12:13]
	v_pk_mul_f32 v[10:11], v[14:15], v[10:11]
	s_cselect_b32 s53, s30, 0x19c00
	v_cvt_pk_bf16_f32 v19, v16, v17
	v_lshlrev_b32_e32 v16, 1, v143
	s_cselect_b32 s78, 0x12a00, s93
	v_cvt_pk_bf16_f32 v18, v34, v35
	v_add3_u32 v17, s77, v16, v144
	v_cvt_pk_bf16_f32 v12, v12, v13
	v_cvt_pk_bf16_f32 v13, v14, v15
	v_add3_u32 v14, s53, v16, v144
	v_cvt_pk_bf16_f32 v8, v8, v9
	v_cvt_pk_bf16_f32 v9, v10, v11
	ds_write_b64 v17, v[18:19]
	ds_write_b64 v14, v[12:13]
	ds_write_b64 v113, v[8:9] offset:57856
	v_lshl_or_b32 v8, v56, 1, s78
	v_cvt_pk_bf16_f32 v9, v4, s0
	v_add3_u32 v10, v8, v55, v159
	ds_write_b16 v10, v9
	v_cvt_pk_bf16_f32 v9, v5, s0
	ds_write_b16 v10, v9 offset:272
	v_cvt_pk_bf16_f32 v9, v6, s0
	ds_write_b16 v10, v9 offset:544
	v_cvt_pk_bf16_f32 v9, v7, s0
	ds_write_b16 v10, v9 offset:816
	v_cvt_pk_bf16_f32 v9, v0, s0
	v_add3_u32 v8, v8, v153, v159
	ds_write_b16 v8, v9
	v_cvt_pk_bf16_f32 v9, v1, s0
	ds_write_b16 v8, v9 offset:272
	v_cvt_pk_bf16_f32 v9, v2, s0
	ds_write_b16 v8, v9 offset:544
	v_cvt_pk_bf16_f32 v9, v3, s0
	ds_write_b16 v8, v9 offset:816
	v_lshl_add_u64 v[8:9], s[42:43], 0, v[98:99]
	global_store_dwordx2 v[8:9], v[82:83], off
	v_lshl_add_u64 v[8:9], v[78:79], 0, s[70:71]
	s_mov_b32 s30, 0xc0000
	v_add_co_u32_e32 v8, vcc, s30, v8
	v_add_u32_e32 v40, -6, v86
	s_nop 0
	v_addc_co_u32_e32 v9, vcc, 0, v9, vcc
	global_load_dwordx4 v[20:23], v[8:9], off
	global_load_dwordx4 v[16:19], v[8:9], off offset:2048
	v_lshl_add_u64 v[8:9], v[90:91], 0, s[70:71]
	global_load_dwordx4 v[12:15], v[8:9], off
	v_lshl_add_u64 v[8:9], v[80:81], 0, s[70:71]
	v_add_co_u32_e32 v8, vcc, 0xc0000, v8
	v_mov_b32_e32 v172, 0
	s_nop 0
	v_addc_co_u32_e32 v9, vcc, 0, v9, vcc
	global_load_dwordx4 v[24:27], v[8:9], off
	global_load_dwordx4 v[28:31], v[8:9], off offset:2048
	v_lshl_add_u64 v[8:9], v[88:89], 0, s[70:71]
	global_load_dwordx4 v[8:11], v[8:9], off
	v_lshl_add_u64 v[32:33], s[64:65], 0, v[40:41]
	v_mad_u64_u32 v[34:35], s[72:73], v32, s86, v[66:67]
	v_mad_i32_i24 v35, v33, s86, v35
	global_load_ushort v171, v[34:35], off
	v_add_co_u32_e32 v34, vcc, 0x3000, v34
	s_nop 1
	v_addc_co_u32_e32 v35, vcc, 0, v35, vcc
	global_load_ushort v172, v[34:35], off
	v_add_co_u32_e32 v34, vcc, 0x3000, v34
	s_nop 1
	v_addc_co_u32_e32 v35, vcc, 0, v35, vcc
	global_load_ushort v174, v[34:35], off
	v_add_co_u32_e32 v34, vcc, 0x3000, v34
	s_nop 1
	v_addc_co_u32_e32 v35, vcc, 0, v35, vcc
	global_load_ushort v173, v[34:35], off
	v_add_co_u32_e32 v34, vcc, 0x3000, v34
	s_nop 1
	v_addc_co_u32_e32 v35, vcc, 0, v35, vcc
	global_load_ushort v175, v[34:35], off
	v_add_co_u32_e32 v34, vcc, 0x3000, v34
	s_nop 1
	v_addc_co_u32_e32 v35, vcc, 0, v35, vcc
	global_load_ushort v176, v[34:35], off
	v_add_co_u32_e32 v34, vcc, 0x3000, v34
	s_nop 1
	v_addc_co_u32_e32 v35, vcc, 0, v35, vcc
	global_load_ushort v40, v[34:35], off
	v_lshl_add_u64 v[32:33], s[42:43], 0, v[84:85]
	v_add_co_u32_e32 v34, vcc, 0xb280000, v32
	s_add_i32 s30, s97, 1
	s_nop 0
	v_addc_co_u32_e32 v35, vcc, 0, v33, vcc
	global_load_ushort v170, v[34:35], off
	v_add_co_u32_e32 v34, vcc, 0xb282000, v32
	s_cmp_lg_u32 s97, 2
	s_nop 0
	v_addc_co_u32_e32 v35, vcc, 0, v33, vcc
	global_load_ushort v169, v[34:35], off
	v_add_co_u32_e32 v34, vcc, 0xb284000, v32
	s_cselect_b32 s97, s30, 0
	s_nop 0
	v_addc_co_u32_e32 v35, vcc, 0, v33, vcc
	v_add_co_u32_e32 v32, vcc, 0xb286000, v32
	global_load_ushort v168, v[34:35], off
	s_nop 0
	v_addc_co_u32_e32 v33, vcc, 0, v33, vcc
	global_load_ushort v49, v[32:33], off
	s_and_saveexec_b64 s[30:31], s[4:5]
	s_cbranch_execz .LBB0_1049
	v_lshl_add_u64 v[32:33], s[42:43], 0, v[92:93]
	global_load_dword v255, v[32:33], off
	v_mul_f32_e64 v33, v118, -v120
	s_nop 1
	v_mov_b32_dpp v33, v33 row_shr:1 row_mask:0xf bank_mask:0xf bound_ctrl:1
	v_fma_f32 v33, v118, -v120, v33
	s_nop 1
	v_add_f32_dpp v33, v33, v33 row_shr:2 row_mask:0xf bank_mask:0xf bound_ctrl:1
	s_nop 1
	v_add_f32_dpp v33, v33, v33 row_shr:4 row_mask:0xf bank_mask:0xf bound_ctrl:1
	s_nop 1
	v_add_f32_dpp v33, v33, v33 row_shr:8 row_mask:0xf bank_mask:0xf bound_ctrl:1
	s_nop 0
	v_readlane_b32 s72, v33, 15
	v_readlane_b32 s73, v33, 31
	v_readlane_b32 vcc_lo, v33, 47
	v_mov_b32_e32 v34, s72
	v_mov_b32_e32 v35, s73
	v_cndmask_b32_e64 v34, v34, 0, s[26:27]
	v_cndmask_b32_e64 v35, 0, v35, s[24:25]
	v_add_f32_e32 v34, v34, v35
	v_mov_b32_e32 v35, vcc_lo
	v_cndmask_b32_e64 v35, 0, v35, s[22:23]
	v_add_f32_e32 v34, v35, v34
	v_add_f32_e32 v33, v33, v34
	v_lshl_or_b32 v34, s97, 8, v135
	v_add_u32_e32 v35, 0x1e200, v34
	ds_write_b32 v35, v33
	v_add_u32_e32 v33, 0x1e500, v34
	ds_write_b32 v33, v118
